# KV-layout prep items: cache-warming loads of the item's 128 P lines at item start
# baseline (speedup 1.0000x reference)
; __device__ __forceinline__ unsigned cvt_pk_bf16(float lo, float hi) { f32x2_t v = {lo, hi}; bf16x2_t b = __builtin_convertvector(v, bf16x2_t); return __builtin_bit_cast(unsigned, b); }
; __device__ __forceinline__ float bf_lo(unsigned u) { return __uint_as_float(u << 16); }
; __device__ __forceinline__ float bf_hi(unsigned u) { return __uint_as_float(u & 0xffff0000u); }
; __device__ __forceinline__ void prep_items(const Ctx& C, int l, int w0, int nw) {
;     ...
;         for (int it = w0; it < 4 * 512; it += nw) {
;             const int bg = it >> 9, tile = it & 511, b = bg >> 1, g = bg & 1;
;             const size_t tokb = (size_t)b * S_ + 32 * tile;
; #pragma unroll
;             for (int which = 0; which < 2; ++which) {
;                 const int kc = PC_KV + (2 + 2 * which) * 128 + g * 64, vc = kc + 128;
;                 bf16_t* kop = (bf16_t*)(C.ws + (which ? WS_KWIN : WS_KSLC)); bf16_t* vop = (bf16_t*)(C.ws + (which ? WS_VWIN : WS_VSLC));
; #pragma unroll
;                 for (int q = 0; q < 4; ++q) {
;                     const int r = (lane >> 3) + 8 * q, c = lane & 7;
;                     const bf16_t* row = P + (tokb + r) * PP;
;                     u32x4 kv = *(const u32x4*)(row + kc + 8 * c);
;                     if (c < 2) {
;                         const u32x4 pv = *(const u32x4*)(row + kc + 8 * (c ^ 1));
;                         const float* rt = rope + (tokb + r) * 16;
;                         const f32x4 ca = *(const f32x4*)rt, cb2 = *(const f32x4*)(rt + 4), sa = *(const f32x4*)(rt + 8), sb = *(const f32x4*)(rt + 12);
;                         const float cs[8] = {ca.x, ca.y, ca.z, ca.w, cb2.x, cb2.y, cb2.z, cb2.w}, sn[8] = {sa.x, sa.y, sa.z, sa.w, sb.x, sb.y, sb.z, sb.w};
;                         const float mv[8] = {bf_lo(kv.x), bf_hi(kv.x), bf_lo(kv.y), bf_hi(kv.y), bf_lo(kv.z), bf_hi(kv.z), bf_lo(kv.w), bf_hi(kv.w)};
;                         const float pp[8] = {bf_lo(pv.x), bf_hi(pv.x), bf_lo(pv.y), bf_hi(pv.y), bf_lo(pv.z), bf_hi(pv.z), bf_lo(pv.w), bf_hi(pv.w)};
;                         const float sg = (c == 0) ? -1.f : 1.f; float o[8];
; #pragma unroll
;                         for (int e = 0; e < 8; ++e) o[e] = mv[e] * cs[e] + sg * pp[e] * sn[e];
;                         kv.x = cvt_pk_bf16(o[0], o[1]); kv.y = cvt_pk_bf16(o[2], o[3]); kv.z = cvt_pk_bf16(o[4], o[5]); kv.w = cvt_pk_bf16(o[6], o[7]);
.LBB0_480:
	s_ashr_i32 s2, s9, 10
	s_and_b32 s73, s9, 0x1ff
	s_ashr_i32 s3, s2, 31
	s_ashr_i32 s72, s9, 9
	s_lshl_b64 s[12:13], s[2:3], 14
	s_lshl_b32 s2, s73, 5
	s_or_b32 s12, s12, s2
	s_lshl_b32 s2, s72, 7
	s_and_b32 s2, s2, 0x80
	s_add_u32 s16, s30, s2
	s_addc_u32 s17, s31, 0
	s_add_u32 s18, s16, 0x1200
	s_addc_u32 s19, s17, 0
	v_or_b32_e32 v62, s12, v10
	v_mov_b64_e32 v[2:3], s[18:19]
	v_mad_u64_u32 v[2:3], s[2:3], v62, s67, v[2:3]
	v_mad_i32_i24 v3, s13, v233, v3
	v_lshlrev_b32_e32 v0, 1, v12
	v_lshl_add_u64 v[50:51], v[2:3], 0, v[0:1]
	global_load_dwordx4 v[6:9], v[50:51], off
	global_load_dword v98, v[50:51], off offset:256
	global_load_dword v98, v[50:51], off offset:512
	global_load_dword v98, v[50:51], off offset:768
	s_mov_b64 s[2:3], 0xe000
	v_lshl_add_u64 v[100:101], v[50:51], 0, s[2:3]
	global_load_dword v98, v[100:101], off
	global_load_dword v98, v[100:101], off offset:256
	global_load_dword v98, v[100:101], off offset:512
	global_load_dword v98, v[100:101], off offset:768
	v_lshl_add_u64 v[100:101], v[100:101], 0, s[2:3]
	global_load_dword v98, v[100:101], off
	global_load_dword v98, v[100:101], off offset:256
	global_load_dword v98, v[100:101], off offset:512
	global_load_dword v98, v[100:101], off offset:768
	v_lshl_add_u64 v[100:101], v[100:101], 0, s[2:3]
	global_load_dword v98, v[100:101], off
	global_load_dword v98, v[100:101], off offset:256
	global_load_dword v98, v[100:101], off offset:512
	global_load_dword v98, v[100:101], off offset:768
	v_mov_b32_e32 v63, s13
	s_and_saveexec_b64 s[2:3], vcc
	s_xor_b64 s[2:3], exec, s[2:3]
	s_or_saveexec_b64 s[78:79], s[2:3]
	v_lshlrev_b64 v[4:5], 6, v[62:63]
	v_lshlrev_b32_e32 v46, 1, v14
	v_lshl_add_u64 v[48:49], s[22:23], 0, v[4:5]
	s_xor_b64 exec, exec, s[78:79]
	s_cbranch_execz .LBB0_484
	v_mov_b32_e32 v47, v1
	v_lshl_add_u64 v[2:3], v[2:3], 0, v[46:47]
	global_load_dwordx4 v[52:55], v[2:3], off
	global_load_dwordx4 v[56:59], v[48:49], off offset:16
	s_nop 0
	global_load_dwordx4 v[2:5], v[48:49], off offset:48
	global_load_dwordx4 v[64:67], v[48:49], off
	global_load_dwordx4 v[70:73], v[48:49], off offset:32
	s_waitcnt vmcnt(5)
	v_lshlrev_b32_e32 v76, 16, v7
	v_and_b32_e32 v78, 0xffff0000, v7
	v_lshlrev_b32_e32 v60, 16, v6
	v_and_b32_e32 v74, 0xffff0000, v6
	v_lshlrev_b32_e32 v82, 16, v9
	v_and_b32_e32 v6, 0xffff0000, v9
	v_lshlrev_b32_e32 v80, 16, v8
	v_and_b32_e32 v8, 0xffff0000, v8
	s_waitcnt vmcnt(4)
	v_lshlrev_b32_e32 v7, 16, v52
	v_and_b32_e32 v9, 0xffff0000, v52
	v_lshlrev_b32_e32 v25, 16, v53
	v_and_b32_e32 v27, 0xffff0000, v53
	v_and_b32_e32 v31, 0xffff0000, v54
	v_cndmask_b32_e64 v61, v7, -v7, s[0:1]
	s_waitcnt vmcnt(1)
	v_mov_b32_e32 v52, v64
	s_waitcnt vmcnt(0)
	v_mov_b32_e32 v53, v70
	v_lshlrev_b32_e32 v33, 16, v55
	v_and_b32_e32 v35, 0xffff0000, v55
	v_pk_mul_f32 v[52:53], v[52:53], v[60:61]
	v_cndmask_b32_e64 v75, v9, -v9, s[0:1]
	v_mov_b32_e32 v70, v65
	v_cndmask_b32_e64 v77, v25, -v25, s[0:1]
	v_mov_b32_e32 v60, v66
	v_mov_b32_e32 v61, v72
	v_cndmask_b32_e64 v79, v27, -v27, s[0:1]
	v_mov_b32_e32 v72, v67
	v_mov_b32_e32 v67, v2
	v_cndmask_b32_e64 v9, v31, -v31, s[0:1]
	v_mov_b32_e32 v2, v57
	v_lshlrev_b32_e32 v29, 16, v54
	v_pk_mul_f32 v[54:55], v[70:71], v[74:75]
	v_pk_mul_f32 v[60:61], v[60:61], v[76:77]
	v_pk_mul_f32 v[64:65], v[72:73], v[78:79]
	v_pk_mul_f32 v[2:3], v[2:3], v[8:9]
	v_cndmask_b32_e64 v83, v33, -v33, s[0:1]
	v_mov_b32_e32 v8, v58
	v_mov_b32_e32 v9, v4
	v_cndmask_b32_e64 v7, v35, -v35, s[0:1]
	v_mov_b32_e32 v4, v59
	v_cndmask_b32_e64 v81, v29, -v29, s[0:1]
	v_mov_b32_e32 v66, v56
	v_pk_mul_f32 v[56:57], v[8:9], v[82:83]
	v_pk_mul_f32 v[4:5], v[4:5], v[6:7]
	v_mov_b32_e32 v6, v52
	v_mov_b32_e32 v7, v54
	v_mov_b32_e32 v54, v53
	v_mov_b32_e32 v8, v60
	v_mov_b32_e32 v9, v64
	v_mov_b32_e32 v64, v61
	v_pk_mul_f32 v[66:67], v[66:67], v[80:81]
	v_pk_add_f32 v[6:7], v[6:7], v[54:55]
	v_pk_add_f32 v[8:9], v[8:9], v[64:65]
	v_cvt_pk_bf16_f32 v6, v6, v7
	v_cvt_pk_bf16_f32 v7, v8, v9
	v_mov_b32_e32 v8, v66
	v_mov_b32_e32 v9, v2
	v_mov_b32_e32 v2, v67
	v_pk_add_f32 v[2:3], v[8:9], v[2:3]
	s_nop 0
	v_cvt_pk_bf16_f32 v8, v2, v3
	v_mov_b32_e32 v2, v56
	v_mov_b32_e32 v3, v4
	v_mov_b32_e32 v4, v57
	v_pk_add_f32 v[2:3], v[2:3], v[4:5]
	s_nop 0
	v_cvt_pk_bf16_f32 v9, v2, v3
